# EpiLat: 16-byte latent stores (quarter-row lanes exchange halves via permlane32_swap + swizzle) instead of 8-byte stores
# baseline (speedup 1.0000x reference)
.Llat_norope2:
	s_lshl_b32 s0, s28, 9
	s_lshl_b32 s24, s90, 1
	s_or_b32 s0, s0, s24
	v_lshl_or_b32 v130, v146, 3, s0
	v_mad_u32_u24 v130, v0, s46, v130
	s_lshl_b32 s0, s28, 5
	s_lshl_b32 s24, s88, 2
	s_or_b32 s0, s0, s24
	v_mov_b32_e32 v133, s0
	v_mad_u32_u24 v133, v0, s61, v133
	s_mov_b32 vcc_lo, 0xffff0000
	s_mov_b32 vcc_hi, 0xffff0000
	v_lshlrev_b32_e32 v131, 3, v146
	v_add_u32_e32 v130, v130, v131
	v_pk_mul_f32 v[142:143], v[126:127], v[126:127]
	v_pk_fma_f32 v[142:143], v[128:129], v[128:129], v[142:143]
	v_pk_fma_f32 v[142:143], v[122:123], v[122:123], v[142:143]
	v_pk_fma_f32 v[142:143], v[124:125], v[124:125], v[142:143]
	v_cvt_pk_bf16_f32 v126, v126, v127
	v_cvt_pk_bf16_f32 v127, v128, v129
	v_cvt_pk_bf16_f32 v122, v122, v123
	v_cvt_pk_bf16_f32 v123, v124, v125
	v_add_f32_e32 v150, v142, v143
	v_pk_mul_f32 v[148:149], v[118:119], v[118:119]
	v_pk_fma_f32 v[148:149], v[120:121], v[120:121], v[148:149]
	v_pk_fma_f32 v[148:149], v[114:115], v[114:115], v[148:149]
	v_pk_fma_f32 v[148:149], v[116:117], v[116:117], v[148:149]
	v_cvt_pk_bf16_f32 v118, v118, v119
	v_cvt_pk_bf16_f32 v119, v120, v121
	v_cvt_pk_bf16_f32 v114, v114, v115
	v_cvt_pk_bf16_f32 v115, v116, v117
	v_add_f32_e32 v151, v148, v149
	v_pk_mul_f32 v[142:143], v[110:111], v[110:111]
	v_pk_fma_f32 v[142:143], v[112:113], v[112:113], v[142:143]
	v_pk_fma_f32 v[142:143], v[106:107], v[106:107], v[142:143]
	v_pk_fma_f32 v[142:143], v[108:109], v[108:109], v[142:143]
	v_cvt_pk_bf16_f32 v110, v110, v111
	v_cvt_pk_bf16_f32 v111, v112, v113
	v_cvt_pk_bf16_f32 v106, v106, v107
	v_cvt_pk_bf16_f32 v107, v108, v109
	v_add_f32_e32 v152, v142, v143
	v_pk_mul_f32 v[148:149], v[102:103], v[102:103]
	v_pk_fma_f32 v[148:149], v[104:105], v[104:105], v[148:149]
	v_pk_fma_f32 v[148:149], v[98:99], v[98:99], v[148:149]
	v_pk_fma_f32 v[148:149], v[100:101], v[100:101], v[148:149]
	v_cvt_pk_bf16_f32 v102, v102, v103
	v_cvt_pk_bf16_f32 v103, v104, v105
	v_cvt_pk_bf16_f32 v98, v98, v99
	v_cvt_pk_bf16_f32 v99, v100, v101
	v_add_f32_e32 v153, v148, v149
	v_permlane32_swap_b32_e32 v126, v122
	v_permlane32_swap_b32_e32 v127, v123
	v_permlane32_swap_b32_e32 v118, v114
	v_permlane32_swap_b32_e32 v119, v115
	v_permlane32_swap_b32_e32 v110, v106
	v_permlane32_swap_b32_e32 v111, v107
	v_permlane32_swap_b32_e32 v102, v98
	v_permlane32_swap_b32_e32 v103, v99
	v_cndmask_b32_e32 v128, v122, v126, vcc
	v_cndmask_b32_e32 v129, v123, v127, vcc
	v_cndmask_b32_e32 v120, v114, v118, vcc
	v_cndmask_b32_e32 v121, v115, v119, vcc
	v_cndmask_b32_e32 v112, v106, v110, vcc
	v_cndmask_b32_e32 v113, v107, v111, vcc
	v_cndmask_b32_e32 v104, v98, v102, vcc
	v_cndmask_b32_e32 v105, v99, v103, vcc
	ds_swizzle_b32 v124, v128 offset:swizzle(SWAP,16)
	ds_swizzle_b32 v125, v129 offset:swizzle(SWAP,16)
	ds_swizzle_b32 v116, v120 offset:swizzle(SWAP,16)
	ds_swizzle_b32 v117, v121 offset:swizzle(SWAP,16)
	ds_swizzle_b32 v108, v112 offset:swizzle(SWAP,16)
	ds_swizzle_b32 v109, v113 offset:swizzle(SWAP,16)
	ds_swizzle_b32 v100, v104 offset:swizzle(SWAP,16)
	ds_swizzle_b32 v101, v105 offset:swizzle(SWAP,16)
	s_waitcnt lgkmcnt(0)
	v_add_u32_e32 v131, 0x0, v130
	v_cndmask_b32_e32 v126, v126, v124, vcc
	v_cndmask_b32_e32 v127, v127, v125, vcc
	v_cndmask_b32_e32 v128, v124, v122, vcc
	v_cndmask_b32_e32 v129, v125, v123, vcc
	global_store_dwordx4 v131, v[126:129], s[8:9]
	v_cndmask_b32_e32 v118, v118, v116, vcc
	v_cndmask_b32_e32 v119, v119, v117, vcc
	v_cndmask_b32_e32 v120, v116, v114, vcc
	v_cndmask_b32_e32 v121, v117, v115, vcc
	global_store_dwordx4 v131, v[118:121], s[8:9] offset:256
	v_add_u32_e32 v132, 0x6000, v130
	v_cndmask_b32_e32 v110, v110, v108, vcc
	v_cndmask_b32_e32 v111, v111, v109, vcc
	v_cndmask_b32_e32 v112, v108, v106, vcc
	v_cndmask_b32_e32 v113, v109, v107, vcc
	global_store_dwordx4 v132, v[110:113], s[8:9]
	v_cndmask_b32_e32 v102, v102, v100, vcc
	v_cndmask_b32_e32 v103, v103, v101, vcc
	v_cndmask_b32_e32 v104, v100, v98, vcc
	v_cndmask_b32_e32 v105, v101, v99, vcc
	global_store_dwordx4 v132, v[102:105], s[8:9] offset:256
	v_pk_mul_f32 v[142:143], v[94:95], v[94:95]
	v_pk_fma_f32 v[142:143], v[96:97], v[96:97], v[142:143]
	v_pk_fma_f32 v[142:143], v[90:91], v[90:91], v[142:143]
	v_pk_fma_f32 v[142:143], v[92:93], v[92:93], v[142:143]
	v_cvt_pk_bf16_f32 v94, v94, v95
	v_cvt_pk_bf16_f32 v95, v96, v97
	v_cvt_pk_bf16_f32 v90, v90, v91
	v_cvt_pk_bf16_f32 v91, v92, v93
	v_add_f32_e32 v154, v142, v143
	v_pk_mul_f32 v[148:149], v[86:87], v[86:87]
	v_pk_fma_f32 v[148:149], v[88:89], v[88:89], v[148:149]
	v_pk_fma_f32 v[148:149], v[82:83], v[82:83], v[148:149]
	v_pk_fma_f32 v[148:149], v[84:85], v[84:85], v[148:149]
	v_cvt_pk_bf16_f32 v86, v86, v87
	v_cvt_pk_bf16_f32 v87, v88, v89
	v_cvt_pk_bf16_f32 v82, v82, v83
	v_cvt_pk_bf16_f32 v83, v84, v85
	v_add_f32_e32 v155, v148, v149
	v_pk_mul_f32 v[142:143], v[78:79], v[78:79]
	v_pk_fma_f32 v[142:143], v[80:81], v[80:81], v[142:143]
	v_pk_fma_f32 v[142:143], v[74:75], v[74:75], v[142:143]
	v_pk_fma_f32 v[142:143], v[76:77], v[76:77], v[142:143]
	v_cvt_pk_bf16_f32 v78, v78, v79
	v_cvt_pk_bf16_f32 v79, v80, v81
	v_cvt_pk_bf16_f32 v74, v74, v75
	v_cvt_pk_bf16_f32 v75, v76, v77
	v_add_f32_e32 v156, v142, v143
	v_pk_mul_f32 v[148:149], v[70:71], v[70:71]
	v_pk_fma_f32 v[148:149], v[72:73], v[72:73], v[148:149]
	v_pk_fma_f32 v[148:149], v[66:67], v[66:67], v[148:149]
	v_pk_fma_f32 v[148:149], v[68:69], v[68:69], v[148:149]
	v_cvt_pk_bf16_f32 v70, v70, v71
	v_cvt_pk_bf16_f32 v71, v72, v73
	v_cvt_pk_bf16_f32 v66, v66, v67
	v_cvt_pk_bf16_f32 v67, v68, v69
	v_add_f32_e32 v157, v148, v149
	v_permlane32_swap_b32_e32 v94, v90
	v_permlane32_swap_b32_e32 v95, v91
	v_permlane32_swap_b32_e32 v86, v82
	v_permlane32_swap_b32_e32 v87, v83
	v_permlane32_swap_b32_e32 v78, v74
	v_permlane32_swap_b32_e32 v79, v75
	v_permlane32_swap_b32_e32 v70, v66
	v_permlane32_swap_b32_e32 v71, v67
	v_cndmask_b32_e32 v96, v90, v94, vcc
	v_cndmask_b32_e32 v97, v91, v95, vcc
	v_cndmask_b32_e32 v88, v82, v86, vcc
	v_cndmask_b32_e32 v89, v83, v87, vcc
	v_cndmask_b32_e32 v80, v74, v78, vcc
	v_cndmask_b32_e32 v81, v75, v79, vcc
	v_cndmask_b32_e32 v72, v66, v70, vcc
	v_cndmask_b32_e32 v73, v67, v71, vcc
	ds_swizzle_b32 v92, v96 offset:swizzle(SWAP,16)
	ds_swizzle_b32 v93, v97 offset:swizzle(SWAP,16)
	ds_swizzle_b32 v84, v88 offset:swizzle(SWAP,16)
	ds_swizzle_b32 v85, v89 offset:swizzle(SWAP,16)
	ds_swizzle_b32 v76, v80 offset:swizzle(SWAP,16)
	ds_swizzle_b32 v77, v81 offset:swizzle(SWAP,16)
	ds_swizzle_b32 v68, v72 offset:swizzle(SWAP,16)
	ds_swizzle_b32 v69, v73 offset:swizzle(SWAP,16)
	s_waitcnt lgkmcnt(0)
	v_add_u32_e32 v131, 0xc000, v130
	v_cndmask_b32_e32 v94, v94, v92, vcc
	v_cndmask_b32_e32 v95, v95, v93, vcc
	v_cndmask_b32_e32 v96, v92, v90, vcc
	v_cndmask_b32_e32 v97, v93, v91, vcc
	global_store_dwordx4 v131, v[94:97], s[8:9]
	v_cndmask_b32_e32 v86, v86, v84, vcc
	v_cndmask_b32_e32 v87, v87, v85, vcc
	v_cndmask_b32_e32 v88, v84, v82, vcc
	v_cndmask_b32_e32 v89, v85, v83, vcc
	global_store_dwordx4 v131, v[86:89], s[8:9] offset:256
	v_add_u32_e32 v132, 0x12000, v130
	v_cndmask_b32_e32 v78, v78, v76, vcc
	v_cndmask_b32_e32 v79, v79, v77, vcc
	v_cndmask_b32_e32 v80, v76, v74, vcc
	v_cndmask_b32_e32 v81, v77, v75, vcc
	global_store_dwordx4 v132, v[78:81], s[8:9]
	v_cndmask_b32_e32 v70, v70, v68, vcc
	v_cndmask_b32_e32 v71, v71, v69, vcc
	v_cndmask_b32_e32 v72, v68, v66, vcc
	v_cndmask_b32_e32 v73, v69, v67, vcc
	global_store_dwordx4 v132, v[70:73], s[8:9] offset:256
	v_pk_mul_f32 v[142:143], v[62:63], v[62:63]
	v_pk_fma_f32 v[142:143], v[64:65], v[64:65], v[142:143]
	v_pk_fma_f32 v[142:143], v[58:59], v[58:59], v[142:143]
	v_pk_fma_f32 v[142:143], v[60:61], v[60:61], v[142:143]
	v_cvt_pk_bf16_f32 v62, v62, v63
	v_cvt_pk_bf16_f32 v63, v64, v65
	v_cvt_pk_bf16_f32 v58, v58, v59
	v_cvt_pk_bf16_f32 v59, v60, v61
	v_add_f32_e32 v158, v142, v143
	v_pk_mul_f32 v[148:149], v[54:55], v[54:55]
	v_pk_fma_f32 v[148:149], v[56:57], v[56:57], v[148:149]
	v_pk_fma_f32 v[148:149], v[50:51], v[50:51], v[148:149]
	v_pk_fma_f32 v[148:149], v[52:53], v[52:53], v[148:149]
	v_cvt_pk_bf16_f32 v54, v54, v55
	v_cvt_pk_bf16_f32 v55, v56, v57
	v_cvt_pk_bf16_f32 v50, v50, v51
	v_cvt_pk_bf16_f32 v51, v52, v53
	v_add_f32_e32 v159, v148, v149
	v_pk_mul_f32 v[142:143], v[46:47], v[46:47]
	v_pk_fma_f32 v[142:143], v[48:49], v[48:49], v[142:143]
	v_pk_fma_f32 v[142:143], v[42:43], v[42:43], v[142:143]
	v_pk_fma_f32 v[142:143], v[44:45], v[44:45], v[142:143]
	v_cvt_pk_bf16_f32 v46, v46, v47
	v_cvt_pk_bf16_f32 v47, v48, v49
	v_cvt_pk_bf16_f32 v42, v42, v43
	v_cvt_pk_bf16_f32 v43, v44, v45
	v_add_f32_e32 v160, v142, v143
	v_pk_mul_f32 v[148:149], v[38:39], v[38:39]
	v_pk_fma_f32 v[148:149], v[40:41], v[40:41], v[148:149]
	v_pk_fma_f32 v[148:149], v[34:35], v[34:35], v[148:149]
	v_pk_fma_f32 v[148:149], v[36:37], v[36:37], v[148:149]
	v_cvt_pk_bf16_f32 v38, v38, v39
	v_cvt_pk_bf16_f32 v39, v40, v41
	v_cvt_pk_bf16_f32 v34, v34, v35
	v_cvt_pk_bf16_f32 v35, v36, v37
	v_add_f32_e32 v161, v148, v149
	v_permlane32_swap_b32_e32 v62, v58
	v_permlane32_swap_b32_e32 v63, v59
	v_permlane32_swap_b32_e32 v54, v50
	v_permlane32_swap_b32_e32 v55, v51
	v_permlane32_swap_b32_e32 v46, v42
	v_permlane32_swap_b32_e32 v47, v43
	v_permlane32_swap_b32_e32 v38, v34
	v_permlane32_swap_b32_e32 v39, v35
	v_cndmask_b32_e32 v64, v58, v62, vcc
	v_cndmask_b32_e32 v65, v59, v63, vcc
	v_cndmask_b32_e32 v56, v50, v54, vcc
	v_cndmask_b32_e32 v57, v51, v55, vcc
	v_cndmask_b32_e32 v48, v42, v46, vcc
	v_cndmask_b32_e32 v49, v43, v47, vcc
	v_cndmask_b32_e32 v40, v34, v38, vcc
	v_cndmask_b32_e32 v41, v35, v39, vcc
	ds_swizzle_b32 v60, v64 offset:swizzle(SWAP,16)
	ds_swizzle_b32 v61, v65 offset:swizzle(SWAP,16)
	ds_swizzle_b32 v52, v56 offset:swizzle(SWAP,16)
	ds_swizzle_b32 v53, v57 offset:swizzle(SWAP,16)
	ds_swizzle_b32 v44, v48 offset:swizzle(SWAP,16)
	ds_swizzle_b32 v45, v49 offset:swizzle(SWAP,16)
	ds_swizzle_b32 v36, v40 offset:swizzle(SWAP,16)
	ds_swizzle_b32 v37, v41 offset:swizzle(SWAP,16)
	s_waitcnt lgkmcnt(0)
	v_add_u32_e32 v131, 0x30000, v130
	v_cndmask_b32_e32 v62, v62, v60, vcc
	v_cndmask_b32_e32 v63, v63, v61, vcc
	v_cndmask_b32_e32 v64, v60, v58, vcc
	v_cndmask_b32_e32 v65, v61, v59, vcc
	global_store_dwordx4 v131, v[62:65], s[8:9]
	v_cndmask_b32_e32 v54, v54, v52, vcc
	v_cndmask_b32_e32 v55, v55, v53, vcc
	v_cndmask_b32_e32 v56, v52, v50, vcc
	v_cndmask_b32_e32 v57, v53, v51, vcc
	global_store_dwordx4 v131, v[54:57], s[8:9] offset:256
	v_add_u32_e32 v132, 0x36000, v130
	v_cndmask_b32_e32 v46, v46, v44, vcc
	v_cndmask_b32_e32 v47, v47, v45, vcc
	v_cndmask_b32_e32 v48, v44, v42, vcc
	v_cndmask_b32_e32 v49, v45, v43, vcc
	global_store_dwordx4 v132, v[46:49], s[8:9]
	v_cndmask_b32_e32 v38, v38, v36, vcc
	v_cndmask_b32_e32 v39, v39, v37, vcc
	v_cndmask_b32_e32 v40, v36, v34, vcc
	v_cndmask_b32_e32 v41, v37, v35, vcc
	global_store_dwordx4 v132, v[38:41], s[8:9] offset:256
	v_pk_mul_f32 v[142:143], v[30:31], v[30:31]
	v_pk_fma_f32 v[142:143], v[32:33], v[32:33], v[142:143]
	v_pk_fma_f32 v[142:143], v[26:27], v[26:27], v[142:143]
	v_pk_fma_f32 v[142:143], v[28:29], v[28:29], v[142:143]
	v_cvt_pk_bf16_f32 v30, v30, v31
	v_cvt_pk_bf16_f32 v31, v32, v33
	v_cvt_pk_bf16_f32 v26, v26, v27
	v_cvt_pk_bf16_f32 v27, v28, v29
	v_add_f32_e32 v162, v142, v143
	v_pk_mul_f32 v[148:149], v[22:23], v[22:23]
	v_pk_fma_f32 v[148:149], v[24:25], v[24:25], v[148:149]
	v_pk_fma_f32 v[148:149], v[18:19], v[18:19], v[148:149]
	v_pk_fma_f32 v[148:149], v[20:21], v[20:21], v[148:149]
	v_cvt_pk_bf16_f32 v22, v22, v23
	v_cvt_pk_bf16_f32 v23, v24, v25
	v_cvt_pk_bf16_f32 v18, v18, v19
	v_cvt_pk_bf16_f32 v19, v20, v21
	v_add_f32_e32 v163, v148, v149
	v_pk_mul_f32 v[142:143], v[14:15], v[14:15]
	v_pk_fma_f32 v[142:143], v[16:17], v[16:17], v[142:143]
	v_pk_fma_f32 v[142:143], v[10:11], v[10:11], v[142:143]
	v_pk_fma_f32 v[142:143], v[12:13], v[12:13], v[142:143]
	v_cvt_pk_bf16_f32 v14, v14, v15
	v_cvt_pk_bf16_f32 v15, v16, v17
	v_cvt_pk_bf16_f32 v10, v10, v11
	v_cvt_pk_bf16_f32 v11, v12, v13
	v_add_f32_e32 v164, v142, v143
	v_pk_mul_f32 v[148:149], v[6:7], v[6:7]
	v_pk_fma_f32 v[148:149], v[8:9], v[8:9], v[148:149]
	v_pk_fma_f32 v[148:149], v[2:3], v[2:3], v[148:149]
	v_pk_fma_f32 v[148:149], v[4:5], v[4:5], v[148:149]
	v_cvt_pk_bf16_f32 v6, v6, v7
	v_cvt_pk_bf16_f32 v7, v8, v9
	v_cvt_pk_bf16_f32 v2, v2, v3
	v_cvt_pk_bf16_f32 v3, v4, v5
	v_add_f32_e32 v165, v148, v149
	v_permlane32_swap_b32_e32 v30, v26
	v_permlane32_swap_b32_e32 v31, v27
	v_permlane32_swap_b32_e32 v22, v18
	v_permlane32_swap_b32_e32 v23, v19
	v_permlane32_swap_b32_e32 v14, v10
	v_permlane32_swap_b32_e32 v15, v11
	v_permlane32_swap_b32_e32 v6, v2
	v_permlane32_swap_b32_e32 v7, v3
	v_cndmask_b32_e32 v32, v26, v30, vcc
	v_cndmask_b32_e32 v33, v27, v31, vcc
	v_cndmask_b32_e32 v24, v18, v22, vcc
	v_cndmask_b32_e32 v25, v19, v23, vcc
	v_cndmask_b32_e32 v16, v10, v14, vcc
	v_cndmask_b32_e32 v17, v11, v15, vcc
	v_cndmask_b32_e32 v8, v2, v6, vcc
	v_cndmask_b32_e32 v9, v3, v7, vcc
	ds_swizzle_b32 v28, v32 offset:swizzle(SWAP,16)
	ds_swizzle_b32 v29, v33 offset:swizzle(SWAP,16)
	ds_swizzle_b32 v20, v24 offset:swizzle(SWAP,16)
	ds_swizzle_b32 v21, v25 offset:swizzle(SWAP,16)
	ds_swizzle_b32 v12, v16 offset:swizzle(SWAP,16)
	ds_swizzle_b32 v13, v17 offset:swizzle(SWAP,16)
	ds_swizzle_b32 v4, v8 offset:swizzle(SWAP,16)
	ds_swizzle_b32 v5, v9 offset:swizzle(SWAP,16)
	s_waitcnt lgkmcnt(0)
	v_add_u32_e32 v131, 0x3c000, v130
	v_cndmask_b32_e32 v30, v30, v28, vcc
	v_cndmask_b32_e32 v31, v31, v29, vcc
	v_cndmask_b32_e32 v32, v28, v26, vcc
	v_cndmask_b32_e32 v33, v29, v27, vcc
	global_store_dwordx4 v131, v[30:33], s[8:9]
	v_cndmask_b32_e32 v22, v22, v20, vcc
	v_cndmask_b32_e32 v23, v23, v21, vcc
	v_cndmask_b32_e32 v24, v20, v18, vcc
	v_cndmask_b32_e32 v25, v21, v19, vcc
	global_store_dwordx4 v131, v[22:25], s[8:9] offset:256
	v_add_u32_e32 v132, 0x42000, v130
	v_cndmask_b32_e32 v14, v14, v12, vcc
	v_cndmask_b32_e32 v15, v15, v13, vcc
	v_cndmask_b32_e32 v16, v12, v10, vcc
	v_cndmask_b32_e32 v17, v13, v11, vcc
	global_store_dwordx4 v132, v[14:17], s[8:9]
	v_cndmask_b32_e32 v6, v6, v4, vcc
	v_cndmask_b32_e32 v7, v7, v5, vcc
	v_cndmask_b32_e32 v8, v4, v2, vcc
	v_cndmask_b32_e32 v9, v5, v3, vcc
	global_store_dwordx4 v132, v[6:9], s[8:9] offset:256
	ds_swizzle_b32 v166, v150 offset:swizzle(SWAP,16)
	ds_swizzle_b32 v167, v151 offset:swizzle(SWAP,16)
	ds_swizzle_b32 v168, v152 offset:swizzle(SWAP,16)
	ds_swizzle_b32 v169, v153 offset:swizzle(SWAP,16)
	ds_swizzle_b32 v170, v154 offset:swizzle(SWAP,16)
	ds_swizzle_b32 v171, v155 offset:swizzle(SWAP,16)
	ds_swizzle_b32 v172, v156 offset:swizzle(SWAP,16)
	ds_swizzle_b32 v173, v157 offset:swizzle(SWAP,16)
	ds_swizzle_b32 v174, v158 offset:swizzle(SWAP,16)
	ds_swizzle_b32 v175, v159 offset:swizzle(SWAP,16)
	ds_swizzle_b32 v176, v160 offset:swizzle(SWAP,16)
	ds_swizzle_b32 v177, v161 offset:swizzle(SWAP,16)
	ds_swizzle_b32 v178, v162 offset:swizzle(SWAP,16)
	ds_swizzle_b32 v179, v163 offset:swizzle(SWAP,16)
	ds_swizzle_b32 v180, v164 offset:swizzle(SWAP,16)
	ds_swizzle_b32 v181, v165 offset:swizzle(SWAP,16)
	s_waitcnt lgkmcnt(0)
	v_add_f32_e32 v150, v150, v166
	v_add_f32_e32 v151, v151, v167
	v_add_f32_e32 v152, v152, v168
	v_add_f32_e32 v153, v153, v169
	v_add_f32_e32 v154, v154, v170
	v_add_f32_e32 v155, v155, v171
	v_add_f32_e32 v156, v156, v172
	v_add_f32_e32 v157, v157, v173
	v_add_f32_e32 v158, v158, v174
	v_add_f32_e32 v159, v159, v175
	v_add_f32_e32 v160, v160, v176
	v_add_f32_e32 v161, v161, v177
	v_add_f32_e32 v162, v162, v178
	v_add_f32_e32 v163, v163, v179
	v_add_f32_e32 v164, v164, v180
	v_add_f32_e32 v165, v165, v181
	v_mov_b32_e32 v182, v150
	v_mov_b32_e32 v183, v151
	v_mov_b32_e32 v184, v152
	v_mov_b32_e32 v185, v153
	v_mov_b32_e32 v186, v154
	v_mov_b32_e32 v187, v155
	v_mov_b32_e32 v188, v156
	v_mov_b32_e32 v189, v157
	v_mov_b32_e32 v228, v158
	v_mov_b32_e32 v229, v159
	v_mov_b32_e32 v230, v160
	v_mov_b32_e32 v231, v161
	v_mov_b32_e32 v232, v162
	v_mov_b32_e32 v233, v163
	v_mov_b32_e32 v234, v164
	v_mov_b32_e32 v235, v165
	v_permlane32_swap_b32_e32 v150, v182
	v_permlane32_swap_b32_e32 v151, v183
	v_permlane32_swap_b32_e32 v152, v184
	v_permlane32_swap_b32_e32 v153, v185
	v_permlane32_swap_b32_e32 v154, v186
	v_permlane32_swap_b32_e32 v155, v187
	v_permlane32_swap_b32_e32 v156, v188
	v_permlane32_swap_b32_e32 v157, v189
	v_permlane32_swap_b32_e32 v158, v228
	v_permlane32_swap_b32_e32 v159, v229
	v_permlane32_swap_b32_e32 v160, v230
	v_permlane32_swap_b32_e32 v161, v231
	v_permlane32_swap_b32_e32 v162, v232
	v_permlane32_swap_b32_e32 v163, v233
	v_permlane32_swap_b32_e32 v164, v234
	v_permlane32_swap_b32_e32 v165, v235
	v_add_f32_e32 v150, v150, v182
	v_add_f32_e32 v151, v151, v183
	v_add_f32_e32 v152, v152, v184
	v_add_f32_e32 v153, v153, v185
	v_add_f32_e32 v154, v154, v186
	v_add_f32_e32 v155, v155, v187
	v_add_f32_e32 v156, v156, v188
	v_add_f32_e32 v157, v157, v189
	v_add_f32_e32 v158, v158, v228
	v_add_f32_e32 v159, v159, v229
	v_add_f32_e32 v160, v160, v230
	v_add_f32_e32 v161, v161, v231
	v_add_f32_e32 v162, v162, v232
	v_add_f32_e32 v163, v163, v233
	v_add_f32_e32 v164, v164, v234
	v_add_f32_e32 v165, v165, v235
	s_mov_b64 exec, 0xffff
	v_add_u32_e32 v144, 0x0, v133
	global_store_dword v144, v150, s[10:11]
	global_store_dword v144, v151, s[10:11] offset:16
	v_add_u32_e32 v145, 0x600, v133
	global_store_dword v145, v152, s[10:11]
	global_store_dword v145, v153, s[10:11] offset:16
	v_add_u32_e32 v144, 0xc00, v133
	global_store_dword v144, v154, s[10:11]
	global_store_dword v144, v155, s[10:11] offset:16
	v_add_u32_e32 v145, 0x1200, v133
	global_store_dword v145, v156, s[10:11]
	global_store_dword v145, v157, s[10:11] offset:16
	v_add_u32_e32 v144, 0x3000, v133
	global_store_dword v144, v158, s[10:11]
	global_store_dword v144, v159, s[10:11] offset:16
	v_add_u32_e32 v145, 0x3600, v133
	global_store_dword v145, v160, s[10:11]
	global_store_dword v145, v161, s[10:11] offset:16
	v_add_u32_e32 v144, 0x3c00, v133
	global_store_dword v144, v162, s[10:11]
	global_store_dword v144, v163, s[10:11] offset:16
	v_add_u32_e32 v145, 0x4200, v133
	global_store_dword v145, v164, s[10:11]
	global_store_dword v145, v165, s[10:11] offset:16
	s_mov_b64 exec, -1
	v_mov_b64_e32 v[194:195], 0xc0
	v_mov_b64_e32 v[196:197], 0xbf
	v_mov_b64_e32 v[198:199], 0x180
	v_mov_b64_e32 v[200:201], 0x17f
	v_mov_b64_e32 v[202:203], 0x200
	v_mov_b64_e32 v[204:205], 0x1ff
	v_mov_b64_e32 v[206:207], 0x100
	v_mov_b64_e32 v[208:209], 0xff
	v_mov_b32_e32 v221, 0x3e38aa3b
	v_mov_b32_e32 v222, 0x7c
	v_mov_b32_e32 v223, 0x80
	v_mov_b32_e32 v224, 0x42800000
	s_andn2_b64 vcc, exec, s[36:37]
	s_mov_b64 s[24:25], -1
	s_cbranch_vccnz .LBB0_122
